# P0 input conversion: non-temporal hint on the once-read 16-byte input loads
# speedup vs baseline: 1.0461x; 1.0396x over previous
; #define LAS __attribute__((address_space(3)))
; #define LDS_WAIT() asm volatile("s_waitcnt lgkmcnt(0)" ::: "memory")
; __device__ __forceinline__ void transpose_item(const float* W, int ldw, int K, int ncols, bf16_t* WT, int row_off, LAS float* scr, int item, int lane) {
;     const int nblk = ncols / 64, kb = item / nblk, nb = item % nblk, k0 = 64 * kb, n0 = 64 * nb;
;     f32x4 v[16];
; #pragma unroll
;     for (int i = 0; i < 16; ++i) v[i] = *(const f32x4*)(W + (size_t)(k0 + 4 * i + (lane >> 4)) * ldw + n0 + (lane & 15) * 4);
; #pragma unroll
;     for (int i = 0; i < 16; ++i) { LAS float* d = scr + (4 * i + (lane >> 4)) * 65 + (lane & 15) * 4; d[0] = v[i].x; d[1] = v[i].y; d[2] = v[i].z; d[3] = v[i].w; }
;     LDS_WAIT();
; __device__ __forceinline__ void p0_phase(const Args& a, LAS unsigned char* lds) {
;     ...
;     for (int it = gw; it < 3840; it += NGW) {
;         const int l = it / 1920; int r = it % 1920;
;         if (r < 1280) { const int seg = r >> 7, sub = r & 127; const int oseg = (int)((0x2154987630ULL >> (4 * seg)) & 15ULL);
;             transpose_item(a.w_in + (size_t)l * DM * NIN + oseg * 512, NIN, DM, 512, WinT + (size_t)l * NIN * DM, seg * 512, scr, sub, lane); }
;         else if (r < 1664) { r -= 1280; transpose_item(a.w_out + (size_t)l * DMIX * DM, DM, DMIX, DM, WoutT + (size_t)l * DM * DMIX, 0, scr, r, lane); }
;         else { r -= 1664; transpose_item(a.wmem + (size_t)l * DM * DM, DM, DM, DM, WmemT + (size_t)l * DM * DM, 0, scr, r, lane); }
.LBB0_11:
	v_mul_hi_i32 v4, v1, s22
	v_add_u32_e32 v4, v4, v1
	v_lshrrev_b32_e32 v7, 31, v4
	v_ashrrev_i32_e32 v4, 10, v4
	v_add_u32_e32 v10, v4, v7
	v_mul_i32_i24_e32 v4, 0x780, v10
	v_sub_u32_e32 v7, v1, v4
	v_cmp_lt_i32_e32 vcc, s23, v7
	s_and_saveexec_b64 s[18:19], vcc
	s_xor_b64 s[18:19], exec, s[18:19]
	s_cbranch_execz .LBB0_17
	v_cmp_lt_u32_e32 vcc, s24, v7
	s_and_saveexec_b64 s[20:21], vcc
	s_xor_b64 s[20:21], exec, s[20:21]
	s_cbranch_execz .LBB0_14
	v_ashrrev_i32_e32 v11, 31, v10
	v_and_b32_e32 v4, 0xf0, v7
	v_and_b32_e32 v7, 15, v7
	v_lshlrev_b64 v[56:57], 22, v[10:11]
	v_lshlrev_b16_e32 v4, 2, v4
	v_lshlrev_b16_e32 v120, 6, v7
	v_lshl_add_u64 v[56:57], s[70:71], 0, v[56:57]
	v_xor_b32_e32 v9, 0x200, v4
	v_lshlrev_b32_e32 v4, 2, v120
	v_or_b32_sdwa v55, v3, v9 dst_sel:DWORD dst_unused:UNUSED_PAD src0_sel:DWORD src1_sel:WORD_0
	v_lshl_add_u64 v[56:57], v[56:57], 0, v[4:5]
	v_mov_b32_e32 v7, v5
	v_lshl_add_u64 v[56:57], v[56:57], 0, v[6:7]
	v_lshlrev_b32_e32 v4, 12, v55
	v_lshl_add_u64 v[116:117], v[56:57], 0, v[4:5]
	v_add_co_u32_e32 v60, vcc, s25, v116
	v_lshlrev_b64 v[10:11], 21, v[10:11]
	s_nop 0
	v_addc_co_u32_e32 v61, vcc, 0, v117, vcc
	v_add_co_u32_e32 v64, vcc, s26, v116
	global_load_dwordx4 v[56:59], v[116:117], off nt
	s_nop 0
	global_load_dwordx4 v[60:63], v[60:61], off nt
	v_addc_co_u32_e32 v65, vcc, 0, v117, vcc
	v_add_co_u32_e32 v68, vcc, s27, v116
	v_lshl_add_u64 v[10:11], s[8:9], 0, v[10:11]
	s_nop 0
	v_addc_co_u32_e32 v69, vcc, 0, v117, vcc
	v_add_co_u32_e32 v72, vcc, s28, v116
	global_load_dwordx4 v[64:67], v[64:65], off nt
	s_nop 0
	global_load_dwordx4 v[68:71], v[68:69], off nt
	v_addc_co_u32_e32 v73, vcc, 0, v117, vcc
	v_add_co_u32_e32 v76, vcc, s29, v116
	v_lshlrev_b32_sdwa v4, v52, v9 dst_sel:DWORD dst_unused:UNUSED_PAD src0_sel:DWORD src1_sel:WORD_0
	s_nop 0
	v_addc_co_u32_e32 v77, vcc, 0, v117, vcc
	v_add_co_u32_e32 v80, vcc, s33, v116
	global_load_dwordx4 v[72:75], v[72:73], off nt
	s_nop 0
	global_load_dwordx4 v[76:79], v[76:77], off nt
	v_addc_co_u32_e32 v81, vcc, 0, v117, vcc
	v_add_co_u32_e32 v84, vcc, s34, v116
	v_lshl_add_u64 v[10:11], v[10:11], 0, v[4:5]
	s_nop 0
	v_addc_co_u32_e32 v85, vcc, 0, v117, vcc
	v_add_co_u32_e32 v88, vcc, s35, v116
	global_load_dwordx4 v[80:83], v[80:81], off nt
	s_nop 0
	global_load_dwordx4 v[84:87], v[84:85], off nt
	v_addc_co_u32_e32 v89, vcc, 0, v117, vcc
	v_add_co_u32_e32 v92, vcc, s36, v116
	v_mov_b32_e32 v9, v5
	s_nop 0
	v_addc_co_u32_e32 v93, vcc, 0, v117, vcc
	v_add_co_u32_e32 v96, vcc, s37, v116
	global_load_dwordx4 v[88:91], v[88:89], off nt
	s_nop 0
	global_load_dwordx4 v[92:95], v[92:93], off nt
	v_addc_co_u32_e32 v97, vcc, 0, v117, vcc
	v_add_co_u32_e32 v100, vcc, s38, v116
	v_or_b32_e32 v4, v13, v120
	s_nop 0
	v_addc_co_u32_e32 v101, vcc, 0, v117, vcc
	v_add_co_u32_e32 v104, vcc, s39, v116
	global_load_dwordx4 v[96:99], v[96:97], off nt
	s_nop 0
	global_load_dwordx4 v[100:103], v[100:101], off nt
	v_addc_co_u32_e32 v105, vcc, 0, v117, vcc
	v_add_co_u32_e32 v108, vcc, s40, v116
	v_lshl_add_u64 v[10:11], v[10:11], 0, v[8:9]
	s_nop 0
	v_addc_co_u32_e32 v109, vcc, 0, v117, vcc
	global_load_dwordx4 v[104:107], v[104:105], off nt
	s_nop 0
	global_load_dwordx4 v[108:111], v[108:109], off nt
	v_add_co_u32_e32 v112, vcc, s41, v116
	v_lshlrev_b32_e32 v4, 11, v4
	s_nop 0
	v_addc_co_u32_e32 v113, vcc, 0, v117, vcc
	global_load_dwordx4 v[112:115], v[112:113], off nt
	v_add_co_u32_e32 v116, vcc, s42, v116
	s_nop 1
	v_addc_co_u32_e32 v117, vcc, 0, v117, vcc
	global_load_dwordx4 v[116:119], v[116:117], off nt
	s_waitcnt vmcnt(15)
	ds_write2_b32 v12, v56, v57 offset1:1
	ds_write2_b32 v12, v58, v59 offset0:2 offset1:3
	s_waitcnt vmcnt(14)
	ds_write2_b32 v22, v60, v61 offset1:1
	ds_write2_b32 v23, v62, v63 offset1:1
	s_waitcnt vmcnt(13)
	ds_write2_b32 v24, v64, v65 offset1:1
	ds_write2_b32 v25, v66, v67 offset1:1
	s_waitcnt vmcnt(12)
	ds_write2_b32 v26, v68, v69 offset1:1
	ds_write2_b32 v27, v70, v71 offset1:1
	s_waitcnt vmcnt(11)
	ds_write2_b32 v28, v72, v73 offset1:1
	ds_write2_b32 v29, v74, v75 offset1:1
	s_waitcnt vmcnt(10)
	ds_write2_b32 v30, v76, v77 offset1:1
	ds_write2_b32 v31, v78, v79 offset1:1
	s_waitcnt vmcnt(9)
	ds_write2_b32 v32, v80, v81 offset1:1
	ds_write2_b32 v33, v82, v83 offset1:1
	s_waitcnt vmcnt(8)
	ds_write2_b32 v34, v84, v85 offset1:1
	ds_write2_b32 v35, v86, v87 offset1:1
	s_waitcnt vmcnt(7)
	ds_write2_b32 v36, v88, v89 offset1:1
	ds_write2_b32 v37, v90, v91 offset1:1
	s_waitcnt vmcnt(6)
	ds_write2_b32 v38, v92, v93 offset1:1
	ds_write2_b32 v39, v94, v95 offset1:1
	s_waitcnt vmcnt(5)
	ds_write2_b32 v40, v96, v97 offset1:1
	ds_write2_b32 v41, v98, v99 offset1:1
	s_waitcnt vmcnt(4)
	ds_write2_b32 v42, v100, v101 offset1:1
	ds_write2_b32 v43, v102, v103 offset1:1
	s_waitcnt vmcnt(3)
	ds_write2_b32 v44, v104, v105 offset1:1
	ds_write2_b32 v45, v106, v107 offset1:1
	s_waitcnt vmcnt(2)
	ds_write2_b32 v46, v108, v109 offset1:1
	ds_write2_b32 v47, v110, v111 offset1:1
	s_waitcnt vmcnt(1)
	ds_write2_b32 v48, v112, v113 offset1:1
	ds_write2_b32 v49, v114, v115 offset1:1
	s_waitcnt vmcnt(0)
	ds_write2_b32 v50, v116, v117 offset1:1
	ds_write2_b32 v51, v118, v119 offset1:1
	s_waitcnt lgkmcnt(0)
	ds_read2_b32 v[60:61], v14 offset0:65 offset1:73
	ds_read2_b32 v[62:63], v14 offset1:8
	ds_read2_b32 v[64:65], v14 offset0:130 offset1:138
	ds_read2_b32 v[66:67], v14 offset0:195 offset1:203
	ds_read2_b32 v[68:69], v53 offset0:4 offset1:12
	ds_read2_b32 v[70:71], v53 offset0:69 offset1:77
	ds_read2_b32 v[72:73], v53 offset0:134 offset1:142
	ds_read2_b32 v[74:75], v53 offset0:199 offset1:207
	v_lshl_add_u64 v[76:77], v[10:11], 0, v[4:5]
	v_or_b32_e32 v4, v15, v120
	s_waitcnt lgkmcnt(6)
; #define LAS __attribute__((address_space(3)))
; __device__ __forceinline__ unsigned pk2(float lo, float hi) { f32x2_t v = {lo, hi}; bf16x2_t b = __builtin_convertvector(v, bf16x2_t); return __builtin_bit_cast(unsigned, b); }
; __device__ __forceinline__ void transpose_item(const float* W, int ldw, int K, int ncols, bf16_t* WT, int row_off, LAS float* scr, int item, int lane) {
;     ...
;     for (int j = 0; j < 8; ++j) { const int n = (lane >> 3) + 8 * j; const LAS float* s = scr + (8 * c) * 65 + n;
;         u32x4 o; o.x = pk2(s[0 * 65], s[1 * 65]); o.y = pk2(s[2 * 65], s[3 * 65]); o.z = pk2(s[4 * 65], s[5 * 65]); o.w = pk2(s[6 * 65], s[7 * 65]);
;         *(u32x4*)(WT + (size_t)(row_off + n0 + n) * K + k0 + 8 * c) = o; }
; __device__ __forceinline__ void p0_phase(const Args& a, LAS unsigned char* lds) {
;     ...
;         if (r < 1280) { const int seg = r >> 7, sub = r & 127; const int oseg = (int)((0x2154987630ULL >> (4 * seg)) & 15ULL);
;             transpose_item(a.w_in + (size_t)l * DM * NIN + oseg * 512, NIN, DM, 512, WinT + (size_t)l * NIN * DM, seg * 512, scr, sub, lane); }
;         else if (r < 1664) { r -= 1280; transpose_item(a.w_out + (size_t)l * DMIX * DM, DM, DMIX, DM, WoutT + (size_t)l * DM * DMIX, 0, scr, r, lane); }
	v_cvt_pk_bf16_f32 v56, v62, v60
	s_waitcnt lgkmcnt(4)
	v_cvt_pk_bf16_f32 v57, v64, v66
	s_waitcnt lgkmcnt(2)
	v_cvt_pk_bf16_f32 v58, v68, v70
	s_waitcnt lgkmcnt(0)
	v_cvt_pk_bf16_f32 v59, v72, v74
	v_lshlrev_b32_e32 v4, 11, v4
	global_store_dwordx4 v[76:77], v[56:59], off
	s_nop 1
	v_cvt_pk_bf16_f32 v56, v63, v61
	v_cvt_pk_bf16_f32 v57, v65, v67
	v_cvt_pk_bf16_f32 v58, v69, v71
	v_cvt_pk_bf16_f32 v59, v73, v75
	v_lshl_add_u64 v[60:61], v[10:11], 0, v[4:5]
	global_store_dwordx4 v[60:61], v[56:59], off
	ds_read2_b32 v[60:61], v14 offset0:81 offset1:89
	ds_read2_b32 v[62:63], v14 offset0:16 offset1:24
	ds_read2_b32 v[64:65], v14 offset0:146 offset1:154
	ds_read2_b32 v[66:67], v14 offset0:211 offset1:219
	ds_read2_b32 v[68:69], v53 offset0:20 offset1:28
	ds_read2_b32 v[70:71], v53 offset0:85 offset1:93
	ds_read2_b32 v[72:73], v53 offset0:150 offset1:158
	ds_read2_b32 v[74:75], v53 offset0:215 offset1:223
	v_or_b32_e32 v4, v16, v120
	v_lshlrev_b32_e32 v4, 11, v4
	v_lshl_add_u64 v[76:77], v[10:11], 0, v[4:5]
	v_or_b32_e32 v4, v17, v120
	s_waitcnt lgkmcnt(6)
	v_cvt_pk_bf16_f32 v56, v62, v60
	s_waitcnt lgkmcnt(4)
	v_cvt_pk_bf16_f32 v57, v64, v66
	s_waitcnt lgkmcnt(2)
	v_cvt_pk_bf16_f32 v58, v68, v70
	s_waitcnt lgkmcnt(0)
	v_cvt_pk_bf16_f32 v59, v72, v74
	v_lshlrev_b32_e32 v4, 11, v4
	global_store_dwordx4 v[76:77], v[56:59], off
	s_nop 1
	v_cvt_pk_bf16_f32 v56, v63, v61
	v_cvt_pk_bf16_f32 v57, v65, v67
	v_cvt_pk_bf16_f32 v58, v69, v71
	v_cvt_pk_bf16_f32 v59, v73, v75
	v_lshl_add_u64 v[60:61], v[10:11], 0, v[4:5]
	global_store_dwordx4 v[60:61], v[56:59], off
	ds_read2_b32 v[60:61], v14 offset0:97 offset1:105
	ds_read2_b32 v[62:63], v14 offset0:32 offset1:40
	ds_read2_b32 v[64:65], v14 offset0:162 offset1:170
	ds_read2_b32 v[66:67], v14 offset0:227 offset1:235
	ds_read2_b32 v[68:69], v53 offset0:36 offset1:44
	ds_read2_b32 v[70:71], v53 offset0:101 offset1:109
	ds_read2_b32 v[72:73], v53 offset0:166 offset1:174
	ds_read2_b32 v[74:75], v53 offset0:231 offset1:239
	v_or_b32_e32 v4, v18, v120
	v_lshlrev_b32_e32 v4, 11, v4
	v_lshl_add_u64 v[76:77], v[10:11], 0, v[4:5]
	v_or_b32_e32 v4, v19, v120
	s_waitcnt lgkmcnt(6)
	v_cvt_pk_bf16_f32 v56, v62, v60
	s_waitcnt lgkmcnt(4)
	v_cvt_pk_bf16_f32 v57, v64, v66
	s_waitcnt lgkmcnt(2)
	v_cvt_pk_bf16_f32 v58, v68, v70
	s_waitcnt lgkmcnt(0)
	v_cvt_pk_bf16_f32 v59, v72, v74
	v_lshlrev_b32_e32 v4, 11, v4
	global_store_dwordx4 v[76:77], v[56:59], off
	s_nop 1
	v_cvt_pk_bf16_f32 v56, v63, v61
	v_cvt_pk_bf16_f32 v57, v65, v67
	v_cvt_pk_bf16_f32 v58, v69, v71
	v_cvt_pk_bf16_f32 v59, v73, v75
	v_lshl_add_u64 v[60:61], v[10:11], 0, v[4:5]
	global_store_dwordx4 v[60:61], v[56:59], off
	ds_read2_b32 v[60:61], v14 offset0:48 offset1:56
	ds_read2_b32 v[62:63], v14 offset0:113 offset1:121
	ds_read2_b32 v[64:65], v14 offset0:178 offset1:186
	ds_read2_b32 v[66:67], v14 offset0:243 offset1:251
	ds_read2_b32 v[68:69], v53 offset0:52 offset1:60
	ds_read2_b32 v[70:71], v53 offset0:117 offset1:125
	ds_read2_b32 v[72:73], v53 offset0:182 offset1:190
	ds_read2_b32 v[74:75], v53 offset0:247 offset1:255
	v_or_b32_e32 v4, v20, v120
	v_lshlrev_b32_e32 v4, 11, v4
	v_lshl_add_u64 v[76:77], v[10:11], 0, v[4:5]
	v_or_b32_e32 v4, v21, v120
	s_waitcnt lgkmcnt(6)
	v_cvt_pk_bf16_f32 v56, v60, v62
	s_waitcnt lgkmcnt(4)
	v_cvt_pk_bf16_f32 v57, v64, v66
	s_waitcnt lgkmcnt(2)
	v_cvt_pk_bf16_f32 v58, v68, v70
	s_waitcnt lgkmcnt(0)
	v_cvt_pk_bf16_f32 v59, v72, v74
	v_lshlrev_b32_e32 v4, 11, v4
	global_store_dwordx4 v[76:77], v[56:59], off
	v_lshl_add_u64 v[10:11], v[10:11], 0, v[4:5]
	s_nop 0
	v_cvt_pk_bf16_f32 v56, v61, v63
	v_cvt_pk_bf16_f32 v57, v65, v67
	v_cvt_pk_bf16_f32 v58, v69, v71
	v_cvt_pk_bf16_f32 v59, v73, v75
	global_store_dwordx4 v[10:11], v[56:59], off
	s_waitcnt lgkmcnt(0)
.LBB0_14:
	s_andn2_saveexec_b64 s[20:21], s[20:21]
	s_cbranch_execz .LBB0_16
	v_lshlrev_b16_e32 v4, 2, v7
	v_and_b32_e32 v4, 0x1fc0, v4
	v_add_u16_e32 v9, 0xec00, v4
	v_lshlrev_b16_e32 v4, 6, v7
	v_mul_hi_i32_i24_e32 v57, 0x600000, v10
	v_mul_i32_i24_e32 v56, 0x600000, v10
	v_and_b32_e32 v55, 0x3c0, v4
	v_lshl_add_u64 v[56:57], s[90:91], 0, v[56:57]
	v_lshlrev_b32_sdwa v4, v54, v55 dst_sel:DWORD dst_unused:UNUSED_PAD src0_sel:DWORD src1_sel:WORD_0
	v_or_b32_e32 v11, v3, v9
	v_lshl_add_u64 v[56:57], v[56:57], 0, v[4:5]
	v_mov_b32_e32 v7, v5
	v_lshl_add_u64 v[56:57], v[56:57], 0, v[6:7]
	v_lshlrev_b32_e32 v4, 12, v11
	v_lshl_add_u64 v[116:117], v[56:57], 0, v[4:5]
	v_add_co_u32_e32 v60, vcc, s28, v116
	v_mul_hi_i32_i24_e32 v11, 0x300000, v10
	s_nop 0
	v_addc_co_u32_e32 v61, vcc, 0, v117, vcc
	v_add_co_u32_e32 v64, vcc, s25, v116
	global_load_dwordx4 v[56:59], v[116:117], off nt
	s_nop 0
	global_load_dwordx4 v[60:63], v[60:61], off nt
	v_addc_co_u32_e32 v65, vcc, 0, v117, vcc
	v_add_co_u32_e32 v68, vcc, s29, v116
	v_mul_i32_i24_e32 v10, 0x300000, v10
	s_nop 0
	v_addc_co_u32_e32 v69, vcc, 0, v117, vcc
	v_add_co_u32_e32 v72, vcc, s26, v116
	global_load_dwordx4 v[64:67], v[64:65], off nt
	s_nop 0
	global_load_dwordx4 v[68:71], v[68:69], off nt
	v_addc_co_u32_e32 v73, vcc, 0, v117, vcc
	v_add_co_u32_e32 v76, vcc, s33, v116
	v_lshl_add_u64 v[10:11], s[6:7], 0, v[10:11]
	s_nop 0
	v_addc_co_u32_e32 v77, vcc, 0, v117, vcc
	v_add_co_u32_e32 v80, vcc, s27, v116
	global_load_dwordx4 v[72:75], v[72:73], off nt
	s_nop 0
	global_load_dwordx4 v[76:79], v[76:77], off nt
	v_addc_co_u32_e32 v81, vcc, 0, v117, vcc
	v_add_co_u32_e32 v84, vcc, s34, v116
	v_lshlrev_b32_e32 v4, 1, v9
	s_nop 0
	v_addc_co_u32_e32 v85, vcc, 0, v117, vcc
	v_add_co_u32_e32 v88, vcc, s35, v116
	global_load_dwordx4 v[80:83], v[80:81], off nt
	s_nop 0
	global_load_dwordx4 v[84:87], v[84:85], off nt
	v_addc_co_u32_e32 v89, vcc, 0, v117, vcc
	v_add_co_u32_e32 v92, vcc, s39, v116
	v_lshl_add_u64 v[10:11], v[10:11], 0, v[4:5]
	s_nop 0
	v_addc_co_u32_e32 v93, vcc, 0, v117, vcc
	v_add_co_u32_e32 v96, vcc, s36, v116
	global_load_dwordx4 v[88:91], v[88:89], off nt
	s_nop 0
	global_load_dwordx4 v[92:95], v[92:93], off nt
	v_addc_co_u32_e32 v97, vcc, 0, v117, vcc
	v_add_co_u32_e32 v100, vcc, s40, v116
	v_or_b32_sdwa v4, v13, v55 dst_sel:DWORD dst_unused:UNUSED_PAD src0_sel:DWORD src1_sel:WORD_0
	s_nop 0
	v_addc_co_u32_e32 v101, vcc, 0, v117, vcc
	v_add_co_u32_e32 v104, vcc, s37, v116
	global_load_dwordx4 v[96:99], v[96:97], off nt
	s_nop 0
	global_load_dwordx4 v[100:103], v[100:101], off nt
	v_addc_co_u32_e32 v105, vcc, 0, v117, vcc
	v_add_co_u32_e32 v108, vcc, s41, v116
	v_mov_b32_e32 v9, v5
	s_nop 0
	v_addc_co_u32_e32 v109, vcc, 0, v117, vcc
	global_load_dwordx4 v[104:107], v[104:105], off nt
	s_nop 0
	global_load_dwordx4 v[108:111], v[108:109], off nt
	v_add_co_u32_e32 v112, vcc, s38, v116
	v_mul_u32_u24_e32 v4, 0x600, v4
	s_nop 0
	v_addc_co_u32_e32 v113, vcc, 0, v117, vcc
	global_load_dwordx4 v[112:115], v[112:113], off nt
	v_add_co_u32_e32 v116, vcc, s42, v116
	v_lshl_add_u64 v[10:11], v[10:11], 0, v[8:9]
	s_nop 0
	v_addc_co_u32_e32 v117, vcc, 0, v117, vcc
	global_load_dwordx4 v[116:119], v[116:117], off nt
	v_lshlrev_b32_e32 v4, 1, v4
	s_waitcnt vmcnt(15)
; #define LAS __attribute__((address_space(3)))
; __device__ __forceinline__ unsigned pk2(float lo, float hi) { f32x2_t v = {lo, hi}; bf16x2_t b = __builtin_convertvector(v, bf16x2_t); return __builtin_bit_cast(unsigned, b); }
; #define LDS_WAIT() asm volatile("s_waitcnt lgkmcnt(0)" ::: "memory")
; __device__ __forceinline__ void transpose_item(const float* W, int ldw, int K, int ncols, bf16_t* WT, int row_off, LAS float* scr, int item, int lane) {
;     ...
;     for (int i = 0; i < 16; ++i) v[i] = *(const f32x4*)(W + (size_t)(k0 + 4 * i + (lane >> 4)) * ldw + n0 + (lane & 15) * 4);
; #pragma unroll
;     for (int i = 0; i < 16; ++i) { LAS float* d = scr + (4 * i + (lane >> 4)) * 65 + (lane & 15) * 4; d[0] = v[i].x; d[1] = v[i].y; d[2] = v[i].z; d[3] = v[i].w; }
;     LDS_WAIT();
;     const int c = lane & 7;
; #pragma unroll
;     for (int j = 0; j < 8; ++j) { const int n = (lane >> 3) + 8 * j; const LAS float* s = scr + (8 * c) * 65 + n;
;         u32x4 o; o.x = pk2(s[0 * 65], s[1 * 65]); o.y = pk2(s[2 * 65], s[3 * 65]); o.z = pk2(s[4 * 65], s[5 * 65]); o.w = pk2(s[6 * 65], s[7 * 65]);
;         *(u32x4*)(WT + (size_t)(row_off + n0 + n) * K + k0 + 8 * c) = o; }
	ds_write2_b32 v12, v56, v57 offset1:1
	ds_write2_b32 v12, v58, v59 offset0:2 offset1:3
	s_waitcnt vmcnt(14)
	ds_write2_b32 v22, v60, v61 offset1:1
	ds_write2_b32 v23, v62, v63 offset1:1
	s_waitcnt vmcnt(13)
	ds_write2_b32 v24, v64, v65 offset1:1
	ds_write2_b32 v25, v66, v67 offset1:1
	s_waitcnt vmcnt(12)
	ds_write2_b32 v26, v68, v69 offset1:1
	ds_write2_b32 v27, v70, v71 offset1:1
	s_waitcnt vmcnt(11)
	ds_write2_b32 v28, v72, v73 offset1:1
	ds_write2_b32 v29, v74, v75 offset1:1
	s_waitcnt vmcnt(10)
	ds_write2_b32 v30, v76, v77 offset1:1
	ds_write2_b32 v31, v78, v79 offset1:1
	s_waitcnt vmcnt(9)
	ds_write2_b32 v32, v80, v81 offset1:1
	ds_write2_b32 v33, v82, v83 offset1:1
	s_waitcnt vmcnt(8)
	ds_write2_b32 v34, v84, v85 offset1:1
	ds_write2_b32 v35, v86, v87 offset1:1
	s_waitcnt vmcnt(7)
	ds_write2_b32 v36, v88, v89 offset1:1
	ds_write2_b32 v37, v90, v91 offset1:1
	s_waitcnt vmcnt(6)
	ds_write2_b32 v38, v92, v93 offset1:1
	ds_write2_b32 v39, v94, v95 offset1:1
	s_waitcnt vmcnt(5)
	ds_write2_b32 v40, v96, v97 offset1:1
	ds_write2_b32 v41, v98, v99 offset1:1
	s_waitcnt vmcnt(4)
	ds_write2_b32 v42, v100, v101 offset1:1
	ds_write2_b32 v43, v102, v103 offset1:1
	s_waitcnt vmcnt(3)
	ds_write2_b32 v44, v104, v105 offset1:1
	ds_write2_b32 v45, v106, v107 offset1:1
	s_waitcnt vmcnt(2)
	ds_write2_b32 v46, v108, v109 offset1:1
	ds_write2_b32 v47, v110, v111 offset1:1
	s_waitcnt vmcnt(1)
	ds_write2_b32 v48, v112, v113 offset1:1
	ds_write2_b32 v49, v114, v115 offset1:1
	s_waitcnt vmcnt(0)
	ds_write2_b32 v50, v116, v117 offset1:1
	ds_write2_b32 v51, v118, v119 offset1:1
	s_waitcnt lgkmcnt(0)
	ds_read2_b32 v[60:61], v14 offset0:65 offset1:73
	ds_read2_b32 v[62:63], v14 offset1:8
	ds_read2_b32 v[64:65], v14 offset0:130 offset1:138
	ds_read2_b32 v[66:67], v14 offset0:195 offset1:203
	ds_read2_b32 v[68:69], v53 offset0:4 offset1:12
	ds_read2_b32 v[70:71], v53 offset0:69 offset1:77
	ds_read2_b32 v[72:73], v53 offset0:134 offset1:142
	ds_read2_b32 v[74:75], v53 offset0:199 offset1:207
	v_lshl_add_u64 v[76:77], v[10:11], 0, v[4:5]
	v_or_b32_sdwa v4, v15, v55 dst_sel:DWORD dst_unused:UNUSED_PAD src0_sel:DWORD src1_sel:WORD_0
	v_mul_u32_u24_e32 v4, 0x600, v4
	s_waitcnt lgkmcnt(6)
	v_cvt_pk_bf16_f32 v56, v62, v60
	s_waitcnt lgkmcnt(4)
	v_cvt_pk_bf16_f32 v57, v64, v66
	s_waitcnt lgkmcnt(2)
	v_cvt_pk_bf16_f32 v58, v68, v70
	s_waitcnt lgkmcnt(0)
	v_cvt_pk_bf16_f32 v59, v72, v74
	v_lshlrev_b32_e32 v4, 1, v4
	global_store_dwordx4 v[76:77], v[56:59], off
	s_nop 1
	v_cvt_pk_bf16_f32 v56, v63, v61
	v_cvt_pk_bf16_f32 v57, v65, v67
	v_cvt_pk_bf16_f32 v58, v69, v71
	v_cvt_pk_bf16_f32 v59, v73, v75
	v_lshl_add_u64 v[60:61], v[10:11], 0, v[4:5]
	global_store_dwordx4 v[60:61], v[56:59], off
	ds_read2_b32 v[60:61], v14 offset0:16 offset1:24
	ds_read2_b32 v[62:63], v14 offset0:81 offset1:89
	ds_read2_b32 v[64:65], v14 offset0:146 offset1:154
	ds_read2_b32 v[66:67], v14 offset0:211 offset1:219
	ds_read2_b32 v[68:69], v53 offset0:20 offset1:28
	ds_read2_b32 v[70:71], v53 offset0:85 offset1:93
	v_or_b32_sdwa v4, v16, v55 dst_sel:DWORD dst_unused:UNUSED_PAD src0_sel:DWORD src1_sel:WORD_0
	ds_read2_b32 v[72:73], v53 offset0:150 offset1:158
	ds_read2_b32 v[74:75], v53 offset0:215 offset1:223
	v_mul_u32_u24_e32 v4, 0x600, v4
	v_lshlrev_b32_e32 v4, 1, v4
	v_lshl_add_u64 v[76:77], v[10:11], 0, v[4:5]
	v_or_b32_sdwa v4, v17, v55 dst_sel:DWORD dst_unused:UNUSED_PAD src0_sel:DWORD src1_sel:WORD_0
	v_mul_u32_u24_e32 v4, 0x600, v4
	s_waitcnt lgkmcnt(6)
	v_cvt_pk_bf16_f32 v56, v60, v62
	s_waitcnt lgkmcnt(4)
	v_cvt_pk_bf16_f32 v57, v64, v66
	s_waitcnt lgkmcnt(2)
	v_cvt_pk_bf16_f32 v58, v68, v70
	s_waitcnt lgkmcnt(0)
	v_cvt_pk_bf16_f32 v59, v72, v74
	v_lshlrev_b32_e32 v4, 1, v4
	global_store_dwordx4 v[76:77], v[56:59], off
	s_nop 1
	v_cvt_pk_bf16_f32 v56, v61, v63
	v_cvt_pk_bf16_f32 v57, v65, v67
	v_cvt_pk_bf16_f32 v58, v69, v71
	v_cvt_pk_bf16_f32 v59, v73, v75
	v_lshl_add_u64 v[60:61], v[10:11], 0, v[4:5]
	global_store_dwordx4 v[60:61], v[56:59], off
	ds_read2_b32 v[60:61], v14 offset0:32 offset1:40
	ds_read2_b32 v[62:63], v14 offset0:97 offset1:105
	ds_read2_b32 v[64:65], v14 offset0:162 offset1:170
	ds_read2_b32 v[66:67], v14 offset0:227 offset1:235
	ds_read2_b32 v[68:69], v53 offset0:36 offset1:44
	ds_read2_b32 v[70:71], v53 offset0:101 offset1:109
	v_or_b32_sdwa v4, v18, v55 dst_sel:DWORD dst_unused:UNUSED_PAD src0_sel:DWORD src1_sel:WORD_0
	ds_read2_b32 v[72:73], v53 offset0:166 offset1:174
	ds_read2_b32 v[74:75], v53 offset0:231 offset1:239
	v_mul_u32_u24_e32 v4, 0x600, v4
	v_lshlrev_b32_e32 v4, 1, v4
	v_lshl_add_u64 v[76:77], v[10:11], 0, v[4:5]
	v_or_b32_sdwa v4, v19, v55 dst_sel:DWORD dst_unused:UNUSED_PAD src0_sel:DWORD src1_sel:WORD_0
	v_mul_u32_u24_e32 v4, 0x600, v4
	s_waitcnt lgkmcnt(6)
	v_cvt_pk_bf16_f32 v56, v60, v62
	s_waitcnt lgkmcnt(4)
	v_cvt_pk_bf16_f32 v57, v64, v66
	s_waitcnt lgkmcnt(2)
	v_cvt_pk_bf16_f32 v58, v68, v70
	s_waitcnt lgkmcnt(0)
	v_cvt_pk_bf16_f32 v59, v72, v74
	v_lshlrev_b32_e32 v4, 1, v4
	global_store_dwordx4 v[76:77], v[56:59], off
	s_nop 1
	v_cvt_pk_bf16_f32 v56, v61, v63
	v_cvt_pk_bf16_f32 v57, v65, v67
	v_cvt_pk_bf16_f32 v58, v69, v71
	v_cvt_pk_bf16_f32 v59, v73, v75
	v_lshl_add_u64 v[60:61], v[10:11], 0, v[4:5]
	global_store_dwordx4 v[60:61], v[56:59], off
	ds_read2_b32 v[60:61], v14 offset0:48 offset1:56
	ds_read2_b32 v[62:63], v14 offset0:113 offset1:121
	ds_read2_b32 v[64:65], v14 offset0:178 offset1:186
	ds_read2_b32 v[66:67], v14 offset0:243 offset1:251
	ds_read2_b32 v[68:69], v53 offset0:52 offset1:60
	ds_read2_b32 v[70:71], v53 offset0:117 offset1:125
	v_or_b32_sdwa v4, v20, v55 dst_sel:DWORD dst_unused:UNUSED_PAD src0_sel:DWORD src1_sel:WORD_0
	ds_read2_b32 v[72:73], v53 offset0:182 offset1:190
	ds_read2_b32 v[74:75], v53 offset0:247 offset1:255
	v_mul_u32_u24_e32 v4, 0x600, v4
	v_lshlrev_b32_e32 v4, 1, v4
	v_lshl_add_u64 v[76:77], v[10:11], 0, v[4:5]
	v_or_b32_sdwa v4, v21, v55 dst_sel:DWORD dst_unused:UNUSED_PAD src0_sel:DWORD src1_sel:WORD_0
	v_mul_u32_u24_e32 v4, 0x600, v4
	s_waitcnt lgkmcnt(6)
	v_cvt_pk_bf16_f32 v56, v60, v62
	s_waitcnt lgkmcnt(4)
	v_cvt_pk_bf16_f32 v57, v64, v66
	s_waitcnt lgkmcnt(2)
	v_cvt_pk_bf16_f32 v58, v68, v70
	s_waitcnt lgkmcnt(0)
	v_cvt_pk_bf16_f32 v59, v72, v74
	v_lshlrev_b32_e32 v4, 1, v4
	global_store_dwordx4 v[76:77], v[56:59], off
	v_lshl_add_u64 v[10:11], v[10:11], 0, v[4:5]
	s_nop 0
	v_cvt_pk_bf16_f32 v56, v61, v63
	v_cvt_pk_bf16_f32 v57, v65, v67
	v_cvt_pk_bf16_f32 v58, v69, v71
	v_cvt_pk_bf16_f32 v59, v73, v75
	global_store_dwordx4 v[10:11], v[56:59], off
	s_waitcnt lgkmcnt(0)

; #define LAS __attribute__((address_space(3)))
; __device__ __forceinline__ void transpose_item(const float* W, int ldw, int K, int ncols, bf16_t* WT, int row_off, LAS float* scr, int item, int lane) {
;     ...
;     for (int i = 0; i < 16; ++i) v[i] = *(const f32x4*)(W + (size_t)(k0 + 4 * i + (lane >> 4)) * ldw + n0 + (lane & 15) * 4);
; #pragma unroll
;     for (int i = 0; i < 16; ++i) { LAS float* d = scr + (4 * i + (lane >> 4)) * 65 + (lane & 15) * 4; d[0] = v[i].x; d[1] = v[i].y; d[2] = v[i].z; d[3] = v[i].w; }
; __device__ __forceinline__ void p0_phase(const Args& a, LAS unsigned char* lds) {
;     ...
;         if (r < 1280) { const int seg = r >> 7, sub = r & 127; const int oseg = (int)((0x2154987630ULL >> (4 * seg)) & 15ULL);
;             transpose_item(a.w_in + (size_t)l * DM * NIN + oseg * 512, NIN, DM, 512, WinT + (size_t)l * NIN * DM, seg * 512, scr, sub, lane); }
.LBB0_17:
	s_andn2_saveexec_b64 s[18:19], s[18:19]
	s_cbranch_execz .LBB0_10
	v_ashrrev_i32_e32 v9, 7, v7
	v_lshlrev_b32_e32 v4, 2, v9
	v_lshrrev_b64 v[58:59], v4, s[16:17]
	v_mov_b64_e32 v[56:57], s[88:89]
	v_and_b32_e32 v4, 0x1e00, v58
	v_mad_i64_i32 v[56:57], s[20:21], v10, s43, v[56:57]
	v_lshlrev_b32_e32 v4, 2, v4
	v_lshl_add_u64 v[56:57], v[56:57], 0, v[4:5]
	v_and_b32_e32 v4, 7, v7
	v_lshlrev_b16_e32 v7, 3, v7
	v_and_b32_e32 v55, 0x3c0, v7
	v_lshlrev_b16_e32 v120, 6, v4
	v_or_b32_sdwa v11, v3, v55 dst_sel:DWORD dst_unused:UNUSED_PAD src0_sel:DWORD src1_sel:WORD_0
	v_lshlrev_b32_e32 v4, 2, v120
	v_lshl_add_u64 v[56:57], v[56:57], 0, v[4:5]
	v_mov_b32_e32 v7, v5
	v_mul_u32_u24_e32 v4, 0x1400, v11
	v_lshl_add_u64 v[56:57], v[56:57], 0, v[6:7]
	v_lshlrev_b32_e32 v4, 2, v4
	v_lshl_add_u64 v[116:117], v[56:57], 0, v[4:5]
	v_add_co_u32_e32 v56, vcc, s29, v116
	v_lshl_or_b32 v7, v9, 9, v120
	s_nop 0
	v_addc_co_u32_e32 v57, vcc, 0, v117, vcc
	v_add_co_u32_e32 v64, vcc, s37, v116
	global_load_dwordx4 v[56:59], v[56:57], off nt
	s_nop 0
	global_load_dwordx4 v[60:63], v[116:117], off nt
	v_addc_co_u32_e32 v65, vcc, 0, v117, vcc
	v_add_co_u32_e32 v68, vcc, s42, v116
	v_lshlrev_b32_sdwa v4, v52, v55 dst_sel:DWORD dst_unused:UNUSED_PAD src0_sel:DWORD src1_sel:WORD_0
	s_nop 0
	v_addc_co_u32_e32 v69, vcc, 0, v117, vcc
	v_add_co_u32_e32 v72, vcc, s45, v116
	global_load_dwordx4 v[64:67], v[64:65], off nt
	s_nop 0
	global_load_dwordx4 v[68:71], v[68:69], off nt
	v_addc_co_u32_e32 v73, vcc, 0, v117, vcc
	v_add_co_u32_e32 v76, vcc, s46, v116
	v_mov_b32_e32 v9, v5
	s_nop 0
	v_addc_co_u32_e32 v77, vcc, 0, v117, vcc
	v_add_co_u32_e32 v80, vcc, s47, v116
	global_load_dwordx4 v[72:75], v[72:73], off nt
	s_nop 0
	global_load_dwordx4 v[76:79], v[76:77], off nt
	v_addc_co_u32_e32 v81, vcc, 0, v117, vcc
	v_add_co_u32_e32 v84, vcc, s49, v116
	s_nop 1
	v_addc_co_u32_e32 v85, vcc, 0, v117, vcc
	v_add_co_u32_e32 v88, vcc, s50, v116
	global_load_dwordx4 v[80:83], v[80:81], off nt
	s_nop 0
	global_load_dwordx4 v[84:87], v[84:85], off nt
	v_addc_co_u32_e32 v89, vcc, 0, v117, vcc
	v_add_co_u32_e32 v92, vcc, s51, v116
	s_nop 1
	v_addc_co_u32_e32 v93, vcc, 0, v117, vcc
	v_add_co_u32_e32 v96, vcc, s52, v116
	global_load_dwordx4 v[88:91], v[88:89], off nt
	s_nop 0
	global_load_dwordx4 v[92:95], v[92:93], off nt
	v_addc_co_u32_e32 v97, vcc, 0, v117, vcc
	v_add_co_u32_e32 v100, vcc, s53, v116
	s_nop 1
	v_addc_co_u32_e32 v101, vcc, 0, v117, vcc
	v_add_co_u32_e32 v104, vcc, s54, v116
	global_load_dwordx4 v[96:99], v[96:97], off nt
	s_nop 0
	global_load_dwordx4 v[100:103], v[100:101], off nt
	v_addc_co_u32_e32 v105, vcc, 0, v117, vcc
	v_add_co_u32_e32 v108, vcc, s55, v116
	s_nop 1
	v_addc_co_u32_e32 v109, vcc, 0, v117, vcc
	v_add_co_u32_e32 v112, vcc, s56, v116
	global_load_dwordx4 v[104:107], v[104:105], off nt
	s_nop 0
	global_load_dwordx4 v[108:111], v[108:109], off nt
	v_addc_co_u32_e32 v113, vcc, 0, v117, vcc
	v_add_co_u32_e32 v116, vcc, s57, v116
	global_load_dwordx4 v[112:115], v[112:113], off nt
	s_nop 0
	v_addc_co_u32_e32 v117, vcc, 0, v117, vcc
	global_load_dwordx4 v[116:119], v[116:117], off nt
	s_waitcnt vmcnt(14)
	ds_write2_b32 v12, v60, v61 offset1:1
	ds_write2_b32 v12, v62, v63 offset0:2 offset1:3
	ds_write2_b32 v22, v56, v57 offset1:1
	ds_write2_b32 v23, v58, v59 offset1:1
	s_waitcnt vmcnt(13)
	ds_write2_b32 v24, v64, v65 offset1:1
	ds_write2_b32 v25, v66, v67 offset1:1
	s_waitcnt vmcnt(12)
	ds_write2_b32 v26, v68, v69 offset1:1
	ds_write2_b32 v27, v70, v71 offset1:1
	s_waitcnt vmcnt(11)
	ds_write2_b32 v28, v72, v73 offset1:1
	ds_write2_b32 v29, v74, v75 offset1:1
	s_waitcnt vmcnt(10)
	ds_write2_b32 v30, v76, v77 offset1:1
	ds_write2_b32 v31, v78, v79 offset1:1
	s_waitcnt vmcnt(9)
	ds_write2_b32 v32, v80, v81 offset1:1
	ds_write2_b32 v33, v82, v83 offset1:1
	s_waitcnt vmcnt(8)
	ds_write2_b32 v34, v84, v85 offset1:1
	ds_write2_b32 v35, v86, v87 offset1:1
	s_waitcnt vmcnt(7)
	ds_write2_b32 v36, v88, v89 offset1:1
	ds_write2_b32 v37, v90, v91 offset1:1
	s_waitcnt vmcnt(6)
	ds_write2_b32 v38, v92, v93 offset1:1
	ds_write2_b32 v39, v94, v95 offset1:1
	s_waitcnt vmcnt(5)
	ds_write2_b32 v40, v96, v97 offset1:1
	ds_write2_b32 v41, v98, v99 offset1:1
	s_waitcnt vmcnt(4)
	ds_write2_b32 v42, v100, v101 offset1:1
	ds_write2_b32 v43, v102, v103 offset1:1
	s_waitcnt vmcnt(3)
	ds_write2_b32 v44, v104, v105 offset1:1
	ds_write2_b32 v45, v106, v107 offset1:1
	s_waitcnt vmcnt(2)
	ds_write2_b32 v46, v108, v109 offset1:1
	ds_write2_b32 v47, v110, v111 offset1:1
	s_waitcnt vmcnt(1)
	ds_write2_b32 v48, v112, v113 offset1:1
	ds_write2_b32 v49, v114, v115 offset1:1
	s_waitcnt vmcnt(0)
	ds_write2_b32 v50, v116, v117 offset1:1
	ds_write2_b32 v51, v118, v119 offset1:1
	s_waitcnt lgkmcnt(0)
; #define LAS __attribute__((address_space(3)))
; __device__ __forceinline__ unsigned pk2(float lo, float hi) { f32x2_t v = {lo, hi}; bf16x2_t b = __builtin_convertvector(v, bf16x2_t); return __builtin_bit_cast(unsigned, b); }
; #define LDS_WAIT() asm volatile("s_waitcnt lgkmcnt(0)" ::: "memory")
; __device__ __forceinline__ void transpose_item(const float* W, int ldw, int K, int ncols, bf16_t* WT, int row_off, LAS float* scr, int item, int lane) {
;     ...
;     LDS_WAIT();
;     const int c = lane & 7;
; #pragma unroll
;     for (int j = 0; j < 8; ++j) { const int n = (lane >> 3) + 8 * j; const LAS float* s = scr + (8 * c) * 65 + n;
;         u32x4 o; o.x = pk2(s[0 * 65], s[1 * 65]); o.y = pk2(s[2 * 65], s[3 * 65]); o.z = pk2(s[4 * 65], s[5 * 65]); o.w = pk2(s[6 * 65], s[7 * 65]);
;         *(u32x4*)(WT + (size_t)(row_off + n0 + n) * K + k0 + 8 * c) = o; }
	ds_read2_b32 v[60:61], v14 offset0:65 offset1:73
	ds_read2_b32 v[62:63], v14 offset1:8
	ds_read2_b32 v[64:65], v14 offset0:130 offset1:138
	ds_read2_b32 v[66:67], v14 offset0:195 offset1:203
	ds_read2_b32 v[68:69], v53 offset0:4 offset1:12
	ds_read2_b32 v[70:71], v53 offset0:69 offset1:77
	ds_read2_b32 v[72:73], v53 offset0:134 offset1:142
	ds_read2_b32 v[74:75], v53 offset0:199 offset1:207
	v_mov_b64_e32 v[56:57], s[78:79]
	v_mad_i64_i32 v[10:11], s[20:21], v10, s44, v[56:57]
	v_or_b32_e32 v76, v7, v13
	v_lshl_add_u64 v[10:11], v[10:11], 0, v[4:5]
	v_ashrrev_i32_e32 v77, 31, v76
	v_lshl_add_u64 v[10:11], v[10:11], 0, v[8:9]
	v_lshlrev_b64 v[76:77], 11, v[76:77]
	s_waitcnt lgkmcnt(6)
	v_cvt_pk_bf16_f32 v56, v62, v60
	s_waitcnt lgkmcnt(4)
	v_cvt_pk_bf16_f32 v57, v64, v66
	s_waitcnt lgkmcnt(2)
	v_cvt_pk_bf16_f32 v58, v68, v70
	s_waitcnt lgkmcnt(0)
	v_cvt_pk_bf16_f32 v59, v72, v74
	v_lshl_add_u64 v[76:77], v[10:11], 0, v[76:77]
	v_or_b32_e32 v60, v7, v15
	global_store_dwordx4 v[76:77], v[56:59], off
	s_nop 1
	v_cvt_pk_bf16_f32 v56, v63, v61
	v_ashrrev_i32_e32 v61, 31, v60
	v_cvt_pk_bf16_f32 v57, v65, v67
	v_cvt_pk_bf16_f32 v58, v69, v71
	v_cvt_pk_bf16_f32 v59, v73, v75
	v_lshlrev_b64 v[60:61], 11, v[60:61]
	ds_read2_b32 v[62:63], v14 offset0:81 offset1:89
	ds_read2_b32 v[64:65], v14 offset0:16 offset1:24
	ds_read2_b32 v[66:67], v14 offset0:146 offset1:154
	ds_read2_b32 v[68:69], v14 offset0:211 offset1:219
	ds_read2_b32 v[70:71], v53 offset0:20 offset1:28
	ds_read2_b32 v[72:73], v53 offset0:85 offset1:93
	ds_read2_b32 v[74:75], v53 offset0:150 offset1:158
	ds_read2_b32 v[76:77], v53 offset0:215 offset1:223
	v_lshl_add_u64 v[60:61], v[10:11], 0, v[60:61]
	global_store_dwordx4 v[60:61], v[56:59], off
	v_or_b32_e32 v60, v7, v16
	v_ashrrev_i32_e32 v61, 31, v60
	v_lshlrev_b64 v[60:61], 11, v[60:61]
	s_waitcnt lgkmcnt(6)
	v_cvt_pk_bf16_f32 v56, v64, v62
	s_waitcnt lgkmcnt(4)
	v_cvt_pk_bf16_f32 v57, v66, v68
	s_waitcnt lgkmcnt(2)
	v_cvt_pk_bf16_f32 v58, v70, v72
	s_waitcnt lgkmcnt(0)
	v_cvt_pk_bf16_f32 v59, v74, v76
	v_lshl_add_u64 v[60:61], v[10:11], 0, v[60:61]
	global_store_dwordx4 v[60:61], v[56:59], off
	v_or_b32_e32 v60, v7, v17
	v_ashrrev_i32_e32 v61, 31, v60
	v_cvt_pk_bf16_f32 v56, v65, v63
	v_cvt_pk_bf16_f32 v57, v67, v69
	v_cvt_pk_bf16_f32 v58, v71, v73
	v_cvt_pk_bf16_f32 v59, v75, v77
	v_lshlrev_b64 v[60:61], 11, v[60:61]
	ds_read2_b32 v[62:63], v14 offset0:97 offset1:105
	ds_read2_b32 v[64:65], v14 offset0:32 offset1:40
	ds_read2_b32 v[66:67], v14 offset0:162 offset1:170
	ds_read2_b32 v[68:69], v14 offset0:227 offset1:235
	ds_read2_b32 v[70:71], v53 offset0:36 offset1:44
	ds_read2_b32 v[72:73], v53 offset0:101 offset1:109
	ds_read2_b32 v[74:75], v53 offset0:166 offset1:174
	ds_read2_b32 v[76:77], v53 offset0:231 offset1:239
	v_lshl_add_u64 v[60:61], v[10:11], 0, v[60:61]
	global_store_dwordx4 v[60:61], v[56:59], off
	v_or_b32_e32 v60, v7, v18
	v_ashrrev_i32_e32 v61, 31, v60
	v_lshlrev_b64 v[60:61], 11, v[60:61]
	s_waitcnt lgkmcnt(6)
	v_cvt_pk_bf16_f32 v56, v64, v62
	s_waitcnt lgkmcnt(4)
	v_cvt_pk_bf16_f32 v57, v66, v68
	s_waitcnt lgkmcnt(2)
	v_cvt_pk_bf16_f32 v58, v70, v72
	s_waitcnt lgkmcnt(0)
	v_cvt_pk_bf16_f32 v59, v74, v76
	v_lshl_add_u64 v[60:61], v[10:11], 0, v[60:61]
	global_store_dwordx4 v[60:61], v[56:59], off
	v_or_b32_e32 v60, v7, v19
	v_ashrrev_i32_e32 v61, 31, v60
	v_cvt_pk_bf16_f32 v56, v65, v63
	v_cvt_pk_bf16_f32 v57, v67, v69
	v_cvt_pk_bf16_f32 v58, v71, v73
	v_cvt_pk_bf16_f32 v59, v75, v77
	v_lshlrev_b64 v[60:61], 11, v[60:61]
	ds_read2_b32 v[62:63], v14 offset0:48 offset1:56
	ds_read2_b32 v[64:65], v14 offset0:113 offset1:121
	ds_read2_b32 v[66:67], v14 offset0:178 offset1:186
	ds_read2_b32 v[68:69], v14 offset0:243 offset1:251
	ds_read2_b32 v[70:71], v53 offset0:52 offset1:60
	ds_read2_b32 v[72:73], v53 offset0:117 offset1:125
	ds_read2_b32 v[74:75], v53 offset0:182 offset1:190
	ds_read2_b32 v[76:77], v53 offset0:247 offset1:255
	v_lshl_add_u64 v[60:61], v[10:11], 0, v[60:61]
	global_store_dwordx4 v[60:61], v[56:59], off
	v_or_b32_e32 v60, v7, v20
	v_ashrrev_i32_e32 v61, 31, v60
	v_lshlrev_b64 v[60:61], 11, v[60:61]
	s_waitcnt lgkmcnt(6)
	v_cvt_pk_bf16_f32 v56, v62, v64
	s_waitcnt lgkmcnt(4)
	v_cvt_pk_bf16_f32 v57, v66, v68
	s_waitcnt lgkmcnt(2)
	v_cvt_pk_bf16_f32 v58, v70, v72
	s_waitcnt lgkmcnt(0)
	v_cvt_pk_bf16_f32 v59, v74, v76
	v_lshl_add_u64 v[60:61], v[10:11], 0, v[60:61]
	global_store_dwordx4 v[60:61], v[56:59], off
	v_or_b32_e32 v60, v7, v21
	v_ashrrev_i32_e32 v61, 31, v60
	v_lshlrev_b64 v[60:61], 11, v[60:61]
	v_cvt_pk_bf16_f32 v56, v63, v65
	v_cvt_pk_bf16_f32 v57, v67, v69
	v_cvt_pk_bf16_f32 v58, v71, v73
	v_cvt_pk_bf16_f32 v59, v75, v77
	v_lshl_add_u64 v[10:11], v[10:11], 0, v[60:61]
	global_store_dwordx4 v[10:11], v[56:59], off
	s_waitcnt lgkmcnt(0)
	s_branch .LBB0_10

; __device__ __forceinline__ void norm_rows_load(const Args& a, int m0, int NGW, int lane, RowSet& r) {
;     constexpr int NROWS = NTOK + 2 * NMEM;
; #pragma unroll
;     for (int q = 0; q < 4; ++q) { int m = m0 + q * NGW; if (m >= NROWS) m = m0;
;         const float* xrow = (m < NTOK) ? a.x + (size_t)m * DM : a.mem + (size_t)((m - NTOK) & (NMEM - 1)) * DM;
; #pragma unroll
;         for (int j = 0; j < 4; ++j) r.v[q][j] = ((const f32x4*)xrow + lane)[64 * j]; }
; __device__ __forceinline__ void norm_phase(const Args& a) {
;     ...
;     f32x4 gx[4], gm0[4], gm1[4];
; #pragma unroll
;     for (int j = 0; j < 4; ++j) { gx[j] = ((const f32x4*)a.norm_g + lane)[64 * j]; gm0[j] = ((const f32x4*)a.mng + lane)[64 * j]; gm1[j] = ((const f32x4*)(a.mng + DM) + lane)[64 * j]; }
;     RowSet cur; norm_rows_load(a, gw < NROWS ? gw : 0, NGW, lane, cur);
.LBB0_24:
	v_mov_b32_e32 v54, v178
	v_mov_b32_e32 v181, 0
	v_and_b32_e32 v1, 63, v54
	v_lshlrev_b32_e32 v180, 4, v1
	v_lshl_add_u64 v[2:3], s[68:69], 0, v[180:181]
	s_mov_b64 s[4:5], 0x1000
	v_add_co_u32_e32 v52, vcc, 0x1000, v2
	v_lshl_add_u64 v[50:51], v[2:3], 0, s[4:5]
	s_nop 0
	v_addc_co_u32_e32 v53, vcc, 0, v3, vcc
	global_load_dwordx4 v[2:5], v180, s[86:87] nt
	global_load_dwordx4 v[6:9], v180, s[86:87] offset:1024 nt
	global_load_dwordx4 v[10:13], v180, s[68:69] nt
	global_load_dwordx4 v[14:17], v180, s[68:69] offset:1024 nt
	global_load_dwordx4 v[18:21], v[50:51], off offset:1024 nt
	global_load_dwordx4 v[22:25], v[50:51], off offset:2048 nt
	global_load_dwordx4 v[26:29], v180, s[86:87] offset:2048 nt
	global_load_dwordx4 v[30:33], v180, s[86:87] offset:3072 nt
	global_load_dwordx4 v[34:37], v180, s[68:69] offset:2048 nt
	global_load_dwordx4 v[38:41], v180, s[68:69] offset:3072 nt
	global_load_dwordx4 v[42:45], v[52:53], off nt
	global_load_dwordx4 v[46:49], v[50:51], off offset:3072 nt
	v_ashrrev_i32_e32 v179, 6, v54
	v_add_u32_e32 v66, s30, v179
	s_movk_i32 s4, 0x5000
	v_cmp_gt_i32_e32 vcc, s4, v66
	s_movk_i32 s4, 0x3fff
	s_nop 0
	v_cndmask_b32_e32 v50, 0, v66, vcc
	v_cmp_lt_i32_e64 s[4:5], s4, v50
	s_and_saveexec_b64 s[6:7], s[4:5]
	s_xor_b64 s[4:5], exec, s[6:7]
	v_lshlrev_b32_e32 v51, 12, v50
	v_and_b32_e32 v52, 0x7ff000, v51
	v_mov_b32_e32 v53, v181
	v_lshl_add_u64 v[52:53], s[82:83], 0, v[52:53]
	s_andn2_saveexec_b64 s[4:5], s[4:5]
	v_ashrrev_i32_e32 v51, 31, v50
	v_lshlrev_b64 v[52:53], 12, v[50:51]
	v_lshl_add_u64 v[52:53], s[80:81], 0, v[52:53]
	s_or_b64 exec, exec, s[4:5]
	v_mov_b32_e32 v181, 0
	v_lshl_add_u64 v[52:53], v[52:53], 0, v[180:181]
	global_load_dwordx4 v[174:177], v[52:53], off nt
	global_load_dwordx4 v[170:173], v[52:53], off offset:1024 nt
	global_load_dwordx4 v[166:169], v[52:53], off offset:2048 nt
	global_load_dwordx4 v[162:165], v[52:53], off offset:3072 nt
	v_add_u32_e32 v51, s31, v50
	s_movk_i32 s4, 0x4fff
	v_cmp_lt_i32_e64 s[4:5], s4, v51
	s_nop 1
	v_cndmask_b32_e64 v54, v51, v50, s[4:5]
	s_movk_i32 s4, 0x3fff
	v_cmp_lt_i32_e64 s[4:5], s4, v54
	s_and_saveexec_b64 s[6:7], s[4:5]
	s_xor_b64 s[4:5], exec, s[6:7]
	v_lshlrev_b32_e32 v52, 12, v54
	v_and_b32_e32 v52, 0x7ff000, v52
	v_mov_b32_e32 v53, v181
	v_lshl_add_u64 v[52:53], s[82:83], 0, v[52:53]
	s_andn2_saveexec_b64 s[4:5], s[4:5]
	v_ashrrev_i32_e32 v55, 31, v54
	v_lshlrev_b64 v[52:53], 12, v[54:55]
	v_lshl_add_u64 v[52:53], s[80:81], 0, v[52:53]
	s_or_b64 exec, exec, s[4:5]
	v_mov_b32_e32 v181, 0
	v_lshl_add_u64 v[52:53], v[52:53], 0, v[180:181]
	global_load_dwordx4 v[158:161], v[52:53], off nt
	global_load_dwordx4 v[154:157], v[52:53], off offset:1024 nt
	global_load_dwordx4 v[150:153], v[52:53], off offset:2048 nt
	global_load_dwordx4 v[146:149], v[52:53], off offset:3072 nt
	v_add_u32_e32 v51, s31, v51
	s_movk_i32 s4, 0x4fff
	v_cmp_lt_i32_e64 s[4:5], s4, v51
	s_nop 1
	v_cndmask_b32_e64 v54, v51, v50, s[4:5]
	s_movk_i32 s4, 0x3fff
	v_cmp_lt_i32_e64 s[4:5], s4, v54
	s_and_saveexec_b64 s[6:7], s[4:5]
	s_xor_b64 s[4:5], exec, s[6:7]
	v_lshlrev_b32_e32 v52, 12, v54
	v_and_b32_e32 v52, 0x7ff000, v52
	v_mov_b32_e32 v53, v181
	v_lshl_add_u64 v[52:53], s[82:83], 0, v[52:53]
	s_andn2_saveexec_b64 s[4:5], s[4:5]
	v_ashrrev_i32_e32 v55, 31, v54
	v_lshlrev_b64 v[52:53], 12, v[54:55]
	v_lshl_add_u64 v[52:53], s[80:81], 0, v[52:53]
	s_or_b64 exec, exec, s[4:5]
	v_mov_b32_e32 v181, 0
	v_lshl_add_u64 v[52:53], v[52:53], 0, v[180:181]
	global_load_dwordx4 v[142:145], v[52:53], off nt
	global_load_dwordx4 v[122:125], v[52:53], off offset:1024 nt
	global_load_dwordx4 v[118:121], v[52:53], off offset:2048 nt
	global_load_dwordx4 v[98:101], v[52:53], off offset:3072 nt
	v_add_u32_e32 v51, s31, v51
	s_movk_i32 s4, 0x4fff
	v_cmp_lt_i32_e64 s[4:5], s4, v51
	s_nop 1
	v_cndmask_b32_e64 v52, v51, v50, s[4:5]
	s_movk_i32 s4, 0x3fff
	v_cmp_lt_i32_e64 s[4:5], s4, v52
	s_and_saveexec_b64 s[6:7], s[4:5]
	s_xor_b64 s[4:5], exec, s[6:7]
	s_cbranch_execnz .LBB0_39
	s_andn2_saveexec_b64 s[4:5], s[4:5]
	s_cbranch_execnz .LBB0_40

; __device__ __forceinline__ int otid() { int t = threadIdx.x; asm volatile("" : "+v"(t)); return t; }
; __device__ __forceinline__ void norm_rows_load(const Args& a, int m0, int NGW, int lane, RowSet& r) {
;     ...
;     for (int q = 0; q < 4; ++q) { int m = m0 + q * NGW; if (m >= NROWS) m = m0;
;         const float* xrow = (m < NTOK) ? a.x + (size_t)m * DM : a.mem + (size_t)((m - NTOK) & (NMEM - 1)) * DM;
; #pragma unroll
;         for (int j = 0; j < 4; ++j) r.v[q][j] = ((const f32x4*)xrow + lane)[64 * j]; }
; __device__ __forceinline__ void norm_phase(const Args& a) {
;     const int tid = otid(); const int lane = tid & 63, gw = blockIdx.x * 8 + (tid >> 6), NGW = gridDim.x * 8;
;     bf16_t* H = (bf16_t*)(a.ws + WS_H); float* rss = (float*)(a.ws + WS_RSS);
;     constexpr int NROWS = NTOK + 2 * NMEM;
;     f32x4 gx[4], gm0[4], gm1[4];
; #pragma unroll
;     for (int j = 0; j < 4; ++j) { gx[j] = ((const f32x4*)a.norm_g + lane)[64 * j]; gm0[j] = ((const f32x4*)a.mng + lane)[64 * j]; gm1[j] = ((const f32x4*)(a.mng + DM) + lane)[64 * j]; }
;     RowSet cur; norm_rows_load(a, gw < NROWS ? gw : 0, NGW, lane, cur);
;     for (int m0 = gw; m0 < NROWS; m0 += 4 * NGW) {
.LBB0_41:
	v_mov_b32_e32 v181, 0
	v_lshl_add_u64 v[68:69], v[50:51], 0, v[180:181]
	global_load_dwordx4 v[50:53], v[68:69], off offset:3072 nt
	global_load_dwordx4 v[54:57], v[68:69], off offset:2048 nt
	global_load_dwordx4 v[58:61], v[68:69], off offset:1024 nt
	global_load_dwordx4 v[62:65], v[68:69], off nt
	s_add_u32 s16, s78, 0x1e00000
	v_lshlrev_b32_e32 v67, 10, v179
	s_addc_u32 s17, s79, 0
	v_lshl_add_u32 v190, s2, 13, v67
	v_ashrrev_i32_e32 v67, 31, v66
	s_add_u32 s18, s78, 0xfa00000
	v_lshlrev_b64 v[66:67], 11, v[66:67]
	s_mov_b64 s[4:5], 0x1e00000
	s_addc_u32 s19, s79, 0
	s_lshl_b32 s20, s3, 5
	v_lshl_add_u64 v[66:67], s[78:79], 0, v[66:67]
	v_lshlrev_b32_e32 v189, 14, v1
	v_lshl_add_u64 v[182:183], v[66:67], 0, s[4:5]
	s_ashr_i32 s21, s20, 31
	s_add_i32 s4, s2, s3
	s_lshl_b32 s34, s3, 4
	s_mul_i32 s35, s3, 24
	v_mbcnt_lo_u32_b32 v66, -1, 0
	v_cmp_gt_u32_e64 s[22:23], 4, v1
	v_cmp_eq_u32_e64 s[6:7], 0, v1
	s_lshl_b32 s33, s3, 15
	s_lshl_b64 s[24:25], s[20:21], 11
	v_add_u32_e32 v191, s30, v189
	s_lshl_b32 s21, s4, 3
	s_add_i32 s34, s34, s30
	s_add_i32 s35, s35, s30
	s_add_i32 s36, s20, s30
	s_mov_b64 s[26:27], 0
	s_movk_i32 s37, 0x5000
	s_movk_i32 s38, 0x3fff
	s_movk_i32 s39, 0x4fff
	s_movk_i32 s40, 0x4000
	s_movk_i32 s41, 0x800
	v_mbcnt_hi_u32_b32 v192, -1, v66
	v_mov_b32_e32 v193, 0x358637bd
	s_mov_b32 s42, 0xf800000
	v_mov_b32_e32 v194, 0x260
	v_mov_b32_e32 v195, 0xe600000
	v_mov_b32_e32 v196, 0x3e00000
	s_branch .LBB0_43

; __device__ __forceinline__ float wave_sum(float v) {
; #pragma unroll
;     for (int o = 1; o < 64; o <<= 1) v += __shfl_xor(v, o);
;     return v;
; __device__ __forceinline__ void norm_phase(const Args& a) {
;     ...
;     for (int m0 = gw; m0 < NROWS; m0 += 4 * NGW) {
;         float sacc[4];
; #pragma unroll
;         for (int q = 0; q < 4; ++q) { sacc[q] = 0.f;
; #pragma unroll
;             for (int j = 0; j < 4; ++j) sacc[q] += (cur.v[q][j].x * cur.v[q][j].x + cur.v[q][j].y * cur.v[q][j].y) + (cur.v[q][j].z * cur.v[q][j].z + cur.v[q][j].w * cur.v[q][j].w); }
;         asm volatile("" ::: "memory");
;         RowSet nxt; norm_rows_load(a, (m0 + 4 * NGW < NROWS) ? m0 + 4 * NGW : m0, NGW, lane, nxt);
; #pragma unroll
;         for (int q = 0; q < 4; ++q) {
;             int m = m0 + q * NGW; if (m >= NROWS) m = m0;
;             const bool tokrow = m < NTOK; const int qq = (m - NTOK) & (NMEM - 1), l = (m - NTOK) >> 11;
;             bf16_t* op = tokrow ? H + (size_t)m * DM : (bf16_t*)(a.ws + (l ? WS_MEMH1 : WS_MEMH)) + (size_t)qq * DM;
;             const float tot = wave_sum(sacc[q]);
.LBB0_43:
	v_add_u32_e32 v66, s36, v179
	v_add_u32_e32 v197, s30, v179
	v_cmp_gt_i32_e32 vcc, s37, v66
	s_nop 1
	v_cndmask_b32_e32 v126, v197, v66, vcc
	v_cmp_lt_i32_e32 vcc, s38, v126
	s_and_saveexec_b64 s[4:5], vcc
	s_xor_b64 s[4:5], exec, s[4:5]
	v_lshlrev_b32_e32 v66, 12, v126
	v_and_b32_e32 v66, 0x7ff000, v66
	v_mov_b32_e32 v67, v181
	v_lshl_add_u64 v[66:67], s[82:83], 0, v[66:67]
	s_andn2_saveexec_b64 s[4:5], s[4:5]
	v_ashrrev_i32_e32 v127, 31, v126
	v_lshlrev_b64 v[66:67], 12, v[126:127]
	v_lshl_add_u64 v[66:67], s[80:81], 0, v[66:67]
	s_or_b64 exec, exec, s[4:5]
	v_lshl_add_u64 v[78:79], v[66:67], 0, v[180:181]
	global_load_dwordx4 v[66:69], v[78:79], off nt
	global_load_dwordx4 v[70:73], v[78:79], off offset:1024 nt
	global_load_dwordx4 v[74:77], v[78:79], off offset:2048 nt
	s_nop 0
	global_load_dwordx4 v[78:81], v[78:79], off offset:3072 nt
	v_add_u32_e32 v102, s31, v126
	v_cmp_lt_i32_e32 vcc, s39, v102
	s_nop 1
	v_cndmask_b32_e32 v84, v102, v126, vcc
	v_cmp_lt_i32_e32 vcc, s38, v84
	s_and_saveexec_b64 s[4:5], vcc
	s_xor_b64 s[4:5], exec, s[4:5]
	v_lshlrev_b32_e32 v82, 12, v84
	v_and_b32_e32 v82, 0x7ff000, v82
	v_mov_b32_e32 v83, v181
	v_lshl_add_u64 v[82:83], s[82:83], 0, v[82:83]
	s_andn2_saveexec_b64 s[4:5], s[4:5]
	v_ashrrev_i32_e32 v85, 31, v84
	v_lshlrev_b64 v[82:83], 12, v[84:85]
	v_lshl_add_u64 v[82:83], s[80:81], 0, v[82:83]
	s_or_b64 exec, exec, s[4:5]
	v_lshl_add_u64 v[94:95], v[82:83], 0, v[180:181]
	global_load_dwordx4 v[82:85], v[94:95], off nt
	global_load_dwordx4 v[86:89], v[94:95], off offset:1024 nt
	global_load_dwordx4 v[90:93], v[94:95], off offset:2048 nt
	s_nop 0
	global_load_dwordx4 v[94:97], v[94:95], off offset:3072 nt
	v_add_u32_e32 v127, s31, v102
	v_cmp_lt_i32_e32 vcc, s39, v127
	s_nop 1
	v_cndmask_b32_e32 v104, v127, v126, vcc
	v_cmp_lt_i32_e32 vcc, s38, v104
	s_and_saveexec_b64 s[4:5], vcc
	s_xor_b64 s[4:5], exec, s[4:5]
	v_lshlrev_b32_e32 v102, 12, v104
	v_and_b32_e32 v102, 0x7ff000, v102
	v_mov_b32_e32 v103, v181
	v_lshl_add_u64 v[102:103], s[82:83], 0, v[102:103]
	s_andn2_saveexec_b64 s[4:5], s[4:5]
	v_ashrrev_i32_e32 v105, 31, v104
	v_lshlrev_b64 v[102:103], 12, v[104:105]
	v_lshl_add_u64 v[102:103], s[80:81], 0, v[102:103]
	s_or_b64 exec, exec, s[4:5]
	v_lshl_add_u64 v[114:115], v[102:103], 0, v[180:181]
	global_load_dwordx4 v[102:105], v[114:115], off nt
	global_load_dwordx4 v[106:109], v[114:115], off offset:1024 nt
	global_load_dwordx4 v[110:113], v[114:115], off offset:2048 nt
	s_nop 0
	global_load_dwordx4 v[114:117], v[114:115], off offset:3072 nt
	v_add_u32_e32 v127, s31, v127
	v_cmp_lt_i32_e32 vcc, s39, v127
	s_nop 1
	v_cndmask_b32_e32 v128, v127, v126, vcc
	v_cmp_lt_i32_e32 vcc, s38, v128
	s_and_saveexec_b64 s[4:5], vcc
	s_xor_b64 s[4:5], exec, s[4:5]
	v_lshlrev_b32_e32 v126, 12, v128
	v_and_b32_e32 v126, 0x7ff000, v126
	v_mov_b32_e32 v127, v181
	v_lshl_add_u64 v[126:127], s[82:83], 0, v[126:127]
	s_andn2_saveexec_b64 s[4:5], s[4:5]
	v_ashrrev_i32_e32 v129, 31, v128
	v_lshlrev_b64 v[126:127], 12, v[128:129]
	v_lshl_add_u64 v[126:127], s[80:81], 0, v[126:127]
	s_or_b64 exec, exec, s[4:5]
	v_lshl_add_u64 v[138:139], v[126:127], 0, v[180:181]
	global_load_dwordx4 v[126:129], v[138:139], off nt
	global_load_dwordx4 v[130:133], v[138:139], off offset:1024 nt
	global_load_dwordx4 v[134:137], v[138:139], off offset:2048 nt
	s_nop 0
	global_load_dwordx4 v[138:141], v[138:139], off offset:3072 nt
	v_cmp_gt_i32_e64 s[4:5], s40, v197
	v_cmp_lt_i32_e32 vcc, s38, v197
	v_add_u32_e32 v204, 0xffffc000, v197
	v_mov_b64_e32 v[186:187], v[182:183]
	s_and_saveexec_b64 s[28:29], vcc
	v_cmp_gt_u32_e64 s[8:9], s41, v204
	v_mov_b32_e32 v185, v181
	v_and_b32_e32 v186, 0x1ffc00, v190
	v_cndmask_b32_e64 v184, v195, v196, s[8:9]
	v_lshl_add_u64 v[184:185], s[78:79], 0, v[184:185]
	v_lshlrev_b32_e32 v186, 1, v186
	v_mov_b32_e32 v187, v181
	v_lshl_add_u64 v[186:187], v[184:185], 0, v[186:187]
	s_or_b64 exec, exec, s[28:29]
	v_and_b32_e32 v184, 64, v192
	v_add_u32_e32 v184, 64, v184
	v_xor_b32_e32 v185, 1, v192
	v_cmp_lt_i32_e64 s[8:9], v185, v184
	s_waitcnt vmcnt(31)
	v_mul_f32_e32 v188, v177, v177
	v_fmac_f32_e32 v188, v176, v176
	v_cndmask_b32_e64 v185, v192, v185, s[8:9]
	v_lshlrev_b32_e32 v198, 2, v185
	v_mul_f32_e32 v185, v175, v175
	v_fmac_f32_e32 v185, v174, v174
	v_add_f32_e32 v185, v185, v188
	s_waitcnt vmcnt(30)
	v_mul_f32_e32 v188, v171, v171
	v_mul_f32_e32 v199, v173, v173
	v_fmac_f32_e32 v188, v170, v170
	v_fmac_f32_e32 v199, v172, v172
	v_add_f32_e32 v188, v188, v199
	v_add_f32_e32 v185, v188, v185
	s_waitcnt vmcnt(29)
	v_mul_f32_e32 v188, v167, v167
	v_mul_f32_e32 v199, v169, v169
	v_fmac_f32_e32 v188, v166, v166
	v_fmac_f32_e32 v199, v168, v168
	v_add_f32_e32 v188, v188, v199
	v_add_f32_e32 v185, v188, v185
	s_waitcnt vmcnt(28)
	v_mul_f32_e32 v188, v163, v163
	v_mul_f32_e32 v199, v165, v165
	v_fmac_f32_e32 v188, v162, v162
	v_fmac_f32_e32 v199, v164, v164
	v_add_f32_e32 v188, v188, v199
	v_add_f32_e32 v185, v188, v185
	ds_bpermute_b32 v188, v198, v185
	v_xor_b32_e32 v199, 2, v192
	v_cmp_lt_i32_e64 s[8:9], v199, v184
	v_xor_b32_e32 v200, 4, v192
	v_xor_b32_e32 v201, 8, v192
	v_cndmask_b32_e64 v199, v192, v199, s[8:9]
	v_lshlrev_b32_e32 v199, 2, v199
	s_waitcnt lgkmcnt(0)
	v_add_f32_e32 v185, v185, v188
	ds_bpermute_b32 v188, v199, v185
	v_cmp_lt_i32_e64 s[8:9], v200, v184
	v_xor_b32_e32 v202, 16, v192
	v_xor_b32_e32 v203, 32, v192
	v_cndmask_b32_e64 v200, v192, v200, s[8:9]
	v_lshlrev_b32_e32 v200, 2, v200
	s_waitcnt lgkmcnt(0)
	v_add_f32_e32 v185, v185, v188
	ds_bpermute_b32 v188, v200, v185
	v_cmp_lt_i32_e64 s[8:9], v201, v184
	s_waitcnt lgkmcnt(0)
	v_add_f32_e32 v185, v185, v188
	v_cndmask_b32_e64 v201, v192, v201, s[8:9]
	v_lshlrev_b32_e32 v201, 2, v201
	ds_bpermute_b32 v188, v201, v185
	v_cmp_lt_i32_e64 s[8:9], v202, v184
	s_waitcnt lgkmcnt(0)
	v_add_f32_e32 v185, v185, v188
	v_cndmask_b32_e64 v202, v192, v202, s[8:9]
	v_lshlrev_b32_e32 v202, 2, v202
	ds_bpermute_b32 v188, v202, v185
	v_cmp_lt_i32_e64 s[8:9], v203, v184
	s_nop 1
	v_cndmask_b32_e64 v184, v192, v203, s[8:9]
	v_lshlrev_b32_e32 v203, 2, v184
	s_waitcnt lgkmcnt(0)
	v_add_f32_e32 v184, v185, v188
	ds_bpermute_b32 v185, v203, v184
	v_mov_b32_e32 v188, 1.0
	s_mov_b64 s[8:9], s[22:23]
	s_waitcnt lgkmcnt(0)
	v_add_f32_e32 v205, v184, v185
	s_and_saveexec_b64 s[28:29], vcc
	s_cbranch_execz .LBB0_63
; __device__ __forceinline__ void norm_phase(const Args& a) {
;     ...
;             const float rr = tokrow ? 1.f : 1.f / sqrtf(tot * (1.f / DM) + EPS);
	v_fmamk_f32 v184, v205, 0x3a800000, v193
	v_mul_f32_e32 v185, 0x4f800000, v184
	v_cmp_gt_f32_e32 vcc, s42, v184
	s_nop 1
	v_cndmask_b32_e32 v184, v184, v185, vcc
	v_sqrt_f32_e32 v185, v184
	s_nop 0
	v_add_u32_e32 v188, -1, v185
	v_fma_f32 v207, -v188, v185, v184
	v_add_u32_e32 v206, 1, v185
	v_cmp_ge_f32_e64 s[8:9], 0, v207
	s_nop 1
	v_cndmask_b32_e64 v188, v185, v188, s[8:9]
	v_fma_f32 v185, -v206, v185, v184
	v_cmp_lt_f32_e64 s[8:9], 0, v185
	s_nop 1
	v_cndmask_b32_e64 v185, v188, v206, s[8:9]
	v_mul_f32_e32 v188, 0x37800000, v185
	v_cndmask_b32_e32 v185, v185, v188, vcc
	v_cmp_class_f32_e32 vcc, v184, v194
	s_nop 1
	v_cndmask_b32_e32 v184, v185, v184, vcc
	v_div_scale_f32 v185, s[8:9], v184, v184, 1.0
	v_rcp_f32_e32 v188, v185
	s_andn2_b64 s[8:9], s[22:23], exec
	v_fma_f32 v206, -v185, v188, 1.0
	v_fmac_f32_e32 v188, v206, v188
	v_div_scale_f32 v206, vcc, 1.0, v184, 1.0
	v_mul_f32_e32 v207, v206, v188
	v_fma_f32 v208, -v185, v207, v206
	v_fmac_f32_e32 v207, v208, v188
	v_fma_f32 v185, -v185, v207, v206
	v_div_fmas_f32 v185, v185, v188, v207
	v_div_fixup_f32 v188, v185, v184, 1.0
